# P10a GEMM epilogue: the 16 per-chunk gate-vector loads (each followed by vmcnt(0)) requested together at the top of the epilogue into v176-239; chunks wait with vmcnt(15)
# speedup vs baseline: 1.0023x; 1.0000x over previous
.LBB0_1036:
	v_lshl_add_u32 v144, s0, 8, v148
	s_lshl_b32 s0, s10, 8
	v_ashrrev_i32_e32 v145, 31, v144
	s_and_b32 s0, s0, 0x300
	v_or_b32_e32 v162, s0, v150
	v_lshlrev_b64 v[146:147], 10, v[144:145]
	s_cmp_lt_u32 s10, 4
	s_cselect_b64 s[40:41], -1, 0
	s_cmp_gt_u32 s10, 3
	v_or_b32_e32 v146, v146, v162
	s_cbranch_scc1 .LBB0_1038
	v_mov_b32_e32 v240, v146
	v_mov_b32_e32 v241, v147
	v_lshl_add_u64 v[242:243], v[240:241], 1, s[8:9]
	global_load_dwordx4 v[176:179], v[242:243], off
	v_or_b32_e32 v240, 0x80, v240
	v_lshl_add_u64 v[242:243], v[240:241], 1, s[8:9]
	global_load_dwordx4 v[180:183], v[242:243], off
	v_or_b32_e32 v240, 16, v144
	v_ashrrev_i32_e32 v241, 31, v240
	v_lshlrev_b64 v[240:241], 10, v[240:241]
	v_or_b32_e32 v240, v240, v162
	v_lshl_add_u64 v[242:243], v[240:241], 1, s[8:9]
	global_load_dwordx4 v[184:187], v[242:243], off
	v_or_b32_e32 v240, 0x80, v240
	v_lshl_add_u64 v[242:243], v[240:241], 1, s[8:9]
	global_load_dwordx4 v[188:191], v[242:243], off
	v_or_b32_e32 v240, 32, v144
	v_ashrrev_i32_e32 v241, 31, v240
	v_lshlrev_b64 v[240:241], 10, v[240:241]
	v_or_b32_e32 v240, v240, v162
	v_lshl_add_u64 v[242:243], v[240:241], 1, s[8:9]
	global_load_dwordx4 v[192:195], v[242:243], off
	v_or_b32_e32 v240, 0x80, v240
	v_lshl_add_u64 v[242:243], v[240:241], 1, s[8:9]
	global_load_dwordx4 v[196:199], v[242:243], off
	v_or_b32_e32 v240, 48, v144
	v_ashrrev_i32_e32 v241, 31, v240
	v_lshlrev_b64 v[240:241], 10, v[240:241]
	v_or_b32_e32 v240, v240, v162
	v_lshl_add_u64 v[242:243], v[240:241], 1, s[8:9]
	global_load_dwordx4 v[200:203], v[242:243], off
	v_or_b32_e32 v240, 0x80, v240
	v_lshl_add_u64 v[242:243], v[240:241], 1, s[8:9]
	global_load_dwordx4 v[204:207], v[242:243], off
	v_lshlrev_b64 v[240:241], 10, v[144:145]
	v_or_b32_e32 v240, v240, v162
	v_lshl_add_u64 v[240:241], v[240:241], 0, s[18:19]
	v_lshl_add_u64 v[242:243], v[240:241], 1, s[8:9]
	global_load_dwordx4 v[208:211], v[242:243], off
	v_or_b32_e32 v240, 0x80, v240
	v_lshl_add_u64 v[242:243], v[240:241], 1, s[8:9]
	global_load_dwordx4 v[212:215], v[242:243], off
	v_lshlrev_b64 v[240:241], 10, v[144:145]
	v_or_b32_e32 v240, v240, v162
	v_lshl_add_u64 v[240:241], v[240:241], 0, s[20:21]
	v_lshl_add_u64 v[242:243], v[240:241], 1, s[8:9]
	global_load_dwordx4 v[216:219], v[242:243], off
	v_or_b32_e32 v240, 0x80, v240
	v_lshl_add_u64 v[242:243], v[240:241], 1, s[8:9]
	global_load_dwordx4 v[220:223], v[242:243], off
	v_lshlrev_b64 v[240:241], 10, v[144:145]
	v_or_b32_e32 v240, v240, v162
	v_lshl_add_u64 v[240:241], v[240:241], 0, s[22:23]
	v_lshl_add_u64 v[242:243], v[240:241], 1, s[8:9]
	global_load_dwordx4 v[224:227], v[242:243], off
	v_or_b32_e32 v240, 0x80, v240
	v_lshl_add_u64 v[242:243], v[240:241], 1, s[8:9]
	global_load_dwordx4 v[228:231], v[242:243], off
	v_lshlrev_b64 v[240:241], 10, v[144:145]
	v_or_b32_e32 v240, v240, v162
	v_lshl_add_u64 v[240:241], v[240:241], 0, s[24:25]
	v_lshl_add_u64 v[242:243], v[240:241], 1, s[8:9]
	global_load_dwordx4 v[232:235], v[242:243], off
	v_or_b32_e32 v240, 0x80, v240
	v_lshl_add_u64 v[242:243], v[240:241], 1, s[8:9]
	global_load_dwordx4 v[236:239], v[242:243], off
	s_waitcnt vmcnt(15)
	v_pk_mov_b32 v[164:165], v[176:177], v[176:177] op_sel:[0,1] op_sel_hi:[0,1]
	v_pk_mov_b32 v[166:167], v[178:179], v[178:179] op_sel:[0,1] op_sel_hi:[0,1]
	v_lshlrev_b32_e32 v168, 16, v164
	v_and_b32_e32 v169, 0xffff0000, v164
	v_lshlrev_b32_e32 v164, 16, v165
	v_and_b32_e32 v165, 0xffff0000, v165
	v_lshlrev_b32_e32 v172, 16, v166
	v_and_b32_e32 v173, 0xffff0000, v166
	v_lshlrev_b32_e32 v166, 16, v167
	v_and_b32_e32 v167, 0xffff0000, v167
	v_pk_mul_f32 v[124:125], v[124:125], v[168:169]
	v_pk_mul_f32 v[126:127], v[126:127], v[164:165]
	v_pk_mul_f32 v[120:121], v[120:121], v[172:173]
	v_pk_mul_f32 v[122:123], v[122:123], v[166:167]
.LBB0_1038:
	v_cvt_pk_bf16_f32 v124, v124, v125
	v_cvt_pk_bf16_f32 v125, v126, v127
	v_cvt_pk_bf16_f32 v126, v120, v121
	v_cvt_pk_bf16_f32 v127, v122, v123
	v_lshl_add_u64 v[120:121], v[146:147], 1, s[2:3]
	global_store_dwordx4 v[120:121], v[124:127], off
	v_cndmask_b32_e64 v120, 0, 1, s[40:41]
	v_cmp_ne_u32_e64 s[0:1], 1, v120
	s_andn2_b64 vcc, exec, s[40:41]
	v_or_b32_e32 v146, 0x80, v146
	s_cbranch_vccnz .LBB0_1040
	s_waitcnt vmcnt(15)
	v_pk_mov_b32 v[120:121], v[180:181], v[180:181] op_sel:[0,1] op_sel_hi:[0,1]
	v_pk_mov_b32 v[122:123], v[182:183], v[182:183] op_sel:[0,1] op_sel_hi:[0,1]
	v_lshlrev_b32_e32 v124, 16, v120
	v_and_b32_e32 v125, 0xffff0000, v120
	v_lshlrev_b32_e32 v120, 16, v121
	v_and_b32_e32 v121, 0xffff0000, v121
	v_lshlrev_b32_e32 v126, 16, v122
	v_and_b32_e32 v127, 0xffff0000, v122
	v_lshlrev_b32_e32 v122, 16, v123
	v_and_b32_e32 v123, 0xffff0000, v123
	v_pk_mul_f32 v[116:117], v[116:117], v[124:125]
	v_pk_mul_f32 v[118:119], v[118:119], v[120:121]
	v_pk_mul_f32 v[112:113], v[112:113], v[126:127]
	v_pk_mul_f32 v[114:115], v[114:115], v[122:123]
.LBB0_1040:
	v_cvt_pk_bf16_f32 v116, v116, v117
	v_cvt_pk_bf16_f32 v117, v118, v119
	v_cvt_pk_bf16_f32 v118, v112, v113
	v_cvt_pk_bf16_f32 v119, v114, v115
	v_lshl_add_u64 v[112:113], v[146:147], 1, s[2:3]
	global_store_dwordx4 v[112:113], v[116:119], off
	v_or_b32_e32 v112, 16, v144
	v_ashrrev_i32_e32 v113, 31, v112
	v_lshlrev_b64 v[112:113], 10, v[112:113]
	s_and_b64 vcc, exec, s[0:1]
	v_or_b32_e32 v112, v112, v162
	s_cbranch_vccnz .LBB0_1042
	s_waitcnt vmcnt(15)
	v_pk_mov_b32 v[114:115], v[184:185], v[184:185] op_sel:[0,1] op_sel_hi:[0,1]
	v_pk_mov_b32 v[116:117], v[186:187], v[186:187] op_sel:[0,1] op_sel_hi:[0,1]
	v_lshlrev_b32_e32 v118, 16, v114
	v_and_b32_e32 v119, 0xffff0000, v114
	v_lshlrev_b32_e32 v114, 16, v115
	v_and_b32_e32 v115, 0xffff0000, v115
	v_lshlrev_b32_e32 v120, 16, v116
	v_and_b32_e32 v121, 0xffff0000, v116
	v_lshlrev_b32_e32 v116, 16, v117
	v_and_b32_e32 v117, 0xffff0000, v117
	v_pk_mul_f32 v[108:109], v[108:109], v[118:119]
	v_pk_mul_f32 v[110:111], v[110:111], v[114:115]
	v_pk_mul_f32 v[104:105], v[104:105], v[120:121]
	v_pk_mul_f32 v[106:107], v[106:107], v[116:117]
.LBB0_1042:
	v_cvt_pk_bf16_f32 v108, v108, v109
	v_cvt_pk_bf16_f32 v109, v110, v111
	v_cvt_pk_bf16_f32 v110, v104, v105
	v_cvt_pk_bf16_f32 v111, v106, v107
	v_lshl_add_u64 v[104:105], v[112:113], 1, s[2:3]
	s_and_b64 vcc, exec, s[0:1]
	v_or_b32_e32 v112, 0x80, v112
	global_store_dwordx4 v[104:105], v[108:111], off
	s_cbranch_vccnz .LBB0_1044
	s_waitcnt vmcnt(15)
	v_pk_mov_b32 v[104:105], v[188:189], v[188:189] op_sel:[0,1] op_sel_hi:[0,1]
	v_pk_mov_b32 v[106:107], v[190:191], v[190:191] op_sel:[0,1] op_sel_hi:[0,1]
	v_lshlrev_b32_e32 v108, 16, v104
	v_and_b32_e32 v109, 0xffff0000, v104
	v_lshlrev_b32_e32 v104, 16, v105
	v_and_b32_e32 v105, 0xffff0000, v105
	v_lshlrev_b32_e32 v110, 16, v106
	v_and_b32_e32 v111, 0xffff0000, v106
	v_lshlrev_b32_e32 v106, 16, v107
	v_and_b32_e32 v107, 0xffff0000, v107
	v_pk_mul_f32 v[100:101], v[100:101], v[108:109]
	v_pk_mul_f32 v[102:103], v[102:103], v[104:105]
	v_pk_mul_f32 v[96:97], v[96:97], v[110:111]
	v_pk_mul_f32 v[98:99], v[98:99], v[106:107]
.LBB0_1044:
	v_cvt_pk_bf16_f32 v100, v100, v101
	v_cvt_pk_bf16_f32 v101, v102, v103
	v_cvt_pk_bf16_f32 v102, v96, v97
	v_cvt_pk_bf16_f32 v103, v98, v99
	v_lshl_add_u64 v[96:97], v[112:113], 1, s[2:3]
	global_store_dwordx4 v[96:97], v[100:103], off
	v_or_b32_e32 v96, 32, v144
	v_ashrrev_i32_e32 v97, 31, v96
	v_lshlrev_b64 v[96:97], 10, v[96:97]
	s_and_b64 vcc, exec, s[0:1]
	v_or_b32_e32 v96, v96, v162
	s_cbranch_vccnz .LBB0_1046
	s_waitcnt vmcnt(15)
	v_pk_mov_b32 v[98:99], v[192:193], v[192:193] op_sel:[0,1] op_sel_hi:[0,1]
	v_pk_mov_b32 v[100:101], v[194:195], v[194:195] op_sel:[0,1] op_sel_hi:[0,1]
	v_lshlrev_b32_e32 v102, 16, v98
	v_and_b32_e32 v103, 0xffff0000, v98
	v_lshlrev_b32_e32 v98, 16, v99
	v_and_b32_e32 v99, 0xffff0000, v99
	v_lshlrev_b32_e32 v104, 16, v100
	v_and_b32_e32 v105, 0xffff0000, v100
	v_lshlrev_b32_e32 v100, 16, v101
	v_and_b32_e32 v101, 0xffff0000, v101
	v_pk_mul_f32 v[92:93], v[92:93], v[102:103]
	v_pk_mul_f32 v[94:95], v[94:95], v[98:99]
	v_pk_mul_f32 v[88:89], v[88:89], v[104:105]
	v_pk_mul_f32 v[90:91], v[90:91], v[100:101]
.LBB0_1046:
	v_cvt_pk_bf16_f32 v92, v92, v93
	v_cvt_pk_bf16_f32 v93, v94, v95
	v_cvt_pk_bf16_f32 v94, v88, v89
	v_cvt_pk_bf16_f32 v95, v90, v91
	v_lshl_add_u64 v[88:89], v[96:97], 1, s[2:3]
	s_and_b64 vcc, exec, s[0:1]
	v_or_b32_e32 v96, 0x80, v96
	global_store_dwordx4 v[88:89], v[92:95], off
	s_cbranch_vccnz .LBB0_1048
	s_waitcnt vmcnt(15)
	v_pk_mov_b32 v[88:89], v[196:197], v[196:197] op_sel:[0,1] op_sel_hi:[0,1]
	v_pk_mov_b32 v[90:91], v[198:199], v[198:199] op_sel:[0,1] op_sel_hi:[0,1]
	v_lshlrev_b32_e32 v92, 16, v88
	v_and_b32_e32 v93, 0xffff0000, v88
	v_lshlrev_b32_e32 v88, 16, v89
	v_and_b32_e32 v89, 0xffff0000, v89
	v_lshlrev_b32_e32 v94, 16, v90
	v_and_b32_e32 v95, 0xffff0000, v90
	v_lshlrev_b32_e32 v90, 16, v91
	v_and_b32_e32 v91, 0xffff0000, v91
	v_pk_mul_f32 v[84:85], v[84:85], v[92:93]
	v_pk_mul_f32 v[86:87], v[86:87], v[88:89]
	v_pk_mul_f32 v[80:81], v[80:81], v[94:95]
	v_pk_mul_f32 v[82:83], v[82:83], v[90:91]
.LBB0_1048:
	v_cvt_pk_bf16_f32 v84, v84, v85
	v_cvt_pk_bf16_f32 v85, v86, v87
	v_cvt_pk_bf16_f32 v86, v80, v81
	v_cvt_pk_bf16_f32 v87, v82, v83
	v_lshl_add_u64 v[80:81], v[96:97], 1, s[2:3]
	global_store_dwordx4 v[80:81], v[84:87], off
	v_or_b32_e32 v80, 48, v144
	v_ashrrev_i32_e32 v81, 31, v80
	v_lshlrev_b64 v[80:81], 10, v[80:81]
	s_and_b64 vcc, exec, s[0:1]
	v_or_b32_e32 v80, v80, v162
	s_cbranch_vccnz .LBB0_1050
	s_waitcnt vmcnt(15)
	v_pk_mov_b32 v[82:83], v[200:201], v[200:201] op_sel:[0,1] op_sel_hi:[0,1]
	v_pk_mov_b32 v[84:85], v[202:203], v[202:203] op_sel:[0,1] op_sel_hi:[0,1]
	v_lshlrev_b32_e32 v86, 16, v82
	v_and_b32_e32 v87, 0xffff0000, v82
	v_lshlrev_b32_e32 v82, 16, v83
	v_and_b32_e32 v83, 0xffff0000, v83
	v_lshlrev_b32_e32 v88, 16, v84
	v_and_b32_e32 v89, 0xffff0000, v84
	v_lshlrev_b32_e32 v84, 16, v85
	v_and_b32_e32 v85, 0xffff0000, v85
	v_pk_mul_f32 v[76:77], v[76:77], v[86:87]
	v_pk_mul_f32 v[78:79], v[78:79], v[82:83]
	v_pk_mul_f32 v[72:73], v[72:73], v[88:89]
	v_pk_mul_f32 v[74:75], v[74:75], v[84:85]
.LBB0_1050:
	v_cvt_pk_bf16_f32 v76, v76, v77
	v_cvt_pk_bf16_f32 v77, v78, v79
	v_cvt_pk_bf16_f32 v78, v72, v73
	v_cvt_pk_bf16_f32 v79, v74, v75
	v_lshl_add_u64 v[72:73], v[80:81], 1, s[2:3]
	s_and_b64 vcc, exec, s[0:1]
	v_or_b32_e32 v80, 0x80, v80
	global_store_dwordx4 v[72:73], v[76:79], off
	s_cbranch_vccnz .LBB0_1052
	s_waitcnt vmcnt(15)
	v_pk_mov_b32 v[72:73], v[204:205], v[204:205] op_sel:[0,1] op_sel_hi:[0,1]
	v_pk_mov_b32 v[74:75], v[206:207], v[206:207] op_sel:[0,1] op_sel_hi:[0,1]
	v_lshlrev_b32_e32 v76, 16, v72
	v_and_b32_e32 v77, 0xffff0000, v72
	v_lshlrev_b32_e32 v72, 16, v73
	v_and_b32_e32 v73, 0xffff0000, v73
	v_lshlrev_b32_e32 v78, 16, v74
	v_and_b32_e32 v79, 0xffff0000, v74
	v_lshlrev_b32_e32 v74, 16, v75
	v_and_b32_e32 v75, 0xffff0000, v75
	v_pk_mul_f32 v[68:69], v[68:69], v[76:77]
	v_pk_mul_f32 v[70:71], v[70:71], v[72:73]
	v_pk_mul_f32 v[64:65], v[64:65], v[78:79]
	v_pk_mul_f32 v[66:67], v[66:67], v[74:75]
.LBB0_1052:
	v_cvt_pk_bf16_f32 v68, v68, v69
	v_cvt_pk_bf16_f32 v69, v70, v71
	v_cvt_pk_bf16_f32 v70, v64, v65
	v_cvt_pk_bf16_f32 v71, v66, v67
	v_lshl_add_u64 v[64:65], v[80:81], 1, s[2:3]
	global_store_dwordx4 v[64:65], v[68:71], off
	v_lshlrev_b64 v[64:65], 10, v[144:145]
	v_or_b32_e32 v64, v64, v162
	s_and_b64 vcc, exec, s[0:1]
	v_lshl_add_u64 v[64:65], v[64:65], 0, s[18:19]
	s_cbranch_vccnz .LBB0_1054
	s_waitcnt vmcnt(15)
	v_pk_mov_b32 v[66:67], v[208:209], v[208:209] op_sel:[0,1] op_sel_hi:[0,1]
	v_pk_mov_b32 v[68:69], v[210:211], v[210:211] op_sel:[0,1] op_sel_hi:[0,1]
	v_lshlrev_b32_e32 v70, 16, v66
	v_and_b32_e32 v71, 0xffff0000, v66
	v_lshlrev_b32_e32 v66, 16, v67
	v_and_b32_e32 v67, 0xffff0000, v67
	v_lshlrev_b32_e32 v72, 16, v68
	v_and_b32_e32 v73, 0xffff0000, v68
	v_lshlrev_b32_e32 v68, 16, v69
	v_and_b32_e32 v69, 0xffff0000, v69
	v_pk_mul_f32 v[60:61], v[60:61], v[70:71]
	v_pk_mul_f32 v[62:63], v[62:63], v[66:67]
	v_pk_mul_f32 v[56:57], v[56:57], v[72:73]
	v_pk_mul_f32 v[58:59], v[58:59], v[68:69]
.LBB0_1054:
	v_cvt_pk_bf16_f32 v60, v60, v61
	v_cvt_pk_bf16_f32 v61, v62, v63
	v_cvt_pk_bf16_f32 v62, v56, v57
	v_cvt_pk_bf16_f32 v63, v58, v59
	v_lshl_add_u64 v[56:57], v[64:65], 1, s[2:3]
	s_and_b64 vcc, exec, s[0:1]
	v_or_b32_e32 v64, 0x80, v64
	global_store_dwordx4 v[56:57], v[60:63], off
	s_cbranch_vccnz .LBB0_1056
	s_waitcnt vmcnt(15)
	v_pk_mov_b32 v[56:57], v[212:213], v[212:213] op_sel:[0,1] op_sel_hi:[0,1]
	v_pk_mov_b32 v[58:59], v[214:215], v[214:215] op_sel:[0,1] op_sel_hi:[0,1]
	v_lshlrev_b32_e32 v60, 16, v56
	v_and_b32_e32 v61, 0xffff0000, v56
	v_lshlrev_b32_e32 v56, 16, v57
	v_and_b32_e32 v57, 0xffff0000, v57
	v_lshlrev_b32_e32 v62, 16, v58
	v_and_b32_e32 v63, 0xffff0000, v58
	v_lshlrev_b32_e32 v58, 16, v59
	v_and_b32_e32 v59, 0xffff0000, v59
	v_pk_mul_f32 v[52:53], v[52:53], v[60:61]
	v_pk_mul_f32 v[54:55], v[54:55], v[56:57]
	v_pk_mul_f32 v[48:49], v[48:49], v[62:63]
	v_pk_mul_f32 v[50:51], v[50:51], v[58:59]
.LBB0_1056:
	v_cvt_pk_bf16_f32 v52, v52, v53
	v_cvt_pk_bf16_f32 v53, v54, v55
	v_cvt_pk_bf16_f32 v54, v48, v49
	v_cvt_pk_bf16_f32 v55, v50, v51
	v_lshl_add_u64 v[48:49], v[64:65], 1, s[2:3]
	global_store_dwordx4 v[48:49], v[52:55], off
	v_lshlrev_b64 v[48:49], 10, v[144:145]
	v_or_b32_e32 v48, v48, v162
	s_and_b64 vcc, exec, s[0:1]
	v_lshl_add_u64 v[48:49], v[48:49], 0, s[20:21]
	s_cbranch_vccnz .LBB0_1058
	s_waitcnt vmcnt(15)
	v_pk_mov_b32 v[50:51], v[216:217], v[216:217] op_sel:[0,1] op_sel_hi:[0,1]
	v_pk_mov_b32 v[52:53], v[218:219], v[218:219] op_sel:[0,1] op_sel_hi:[0,1]
	v_lshlrev_b32_e32 v54, 16, v50
	v_and_b32_e32 v55, 0xffff0000, v50
	v_lshlrev_b32_e32 v50, 16, v51
	v_and_b32_e32 v51, 0xffff0000, v51
	v_lshlrev_b32_e32 v56, 16, v52
	v_and_b32_e32 v57, 0xffff0000, v52
	v_lshlrev_b32_e32 v52, 16, v53
	v_and_b32_e32 v53, 0xffff0000, v53
	v_pk_mul_f32 v[44:45], v[44:45], v[54:55]
	v_pk_mul_f32 v[46:47], v[46:47], v[50:51]
	v_pk_mul_f32 v[40:41], v[40:41], v[56:57]
	v_pk_mul_f32 v[42:43], v[42:43], v[52:53]
.LBB0_1058:
	v_cvt_pk_bf16_f32 v44, v44, v45
	v_cvt_pk_bf16_f32 v45, v46, v47
	v_cvt_pk_bf16_f32 v46, v40, v41
	v_cvt_pk_bf16_f32 v47, v42, v43
	v_lshl_add_u64 v[40:41], v[48:49], 1, s[2:3]
	s_and_b64 vcc, exec, s[0:1]
	v_or_b32_e32 v48, 0x80, v48
	global_store_dwordx4 v[40:41], v[44:47], off
	s_cbranch_vccnz .LBB0_1060
	s_waitcnt vmcnt(15)
	v_pk_mov_b32 v[40:41], v[220:221], v[220:221] op_sel:[0,1] op_sel_hi:[0,1]
	v_pk_mov_b32 v[42:43], v[222:223], v[222:223] op_sel:[0,1] op_sel_hi:[0,1]
	v_lshlrev_b32_e32 v44, 16, v40
	v_and_b32_e32 v45, 0xffff0000, v40
	v_lshlrev_b32_e32 v40, 16, v41
	v_and_b32_e32 v41, 0xffff0000, v41
	v_lshlrev_b32_e32 v46, 16, v42
	v_and_b32_e32 v47, 0xffff0000, v42
	v_lshlrev_b32_e32 v42, 16, v43
	v_and_b32_e32 v43, 0xffff0000, v43
	v_pk_mul_f32 v[36:37], v[36:37], v[44:45]
	v_pk_mul_f32 v[38:39], v[38:39], v[40:41]
	v_pk_mul_f32 v[32:33], v[32:33], v[46:47]
	v_pk_mul_f32 v[34:35], v[34:35], v[42:43]
.LBB0_1060:
	v_cvt_pk_bf16_f32 v36, v36, v37
	v_cvt_pk_bf16_f32 v37, v38, v39
	v_cvt_pk_bf16_f32 v38, v32, v33
	v_cvt_pk_bf16_f32 v39, v34, v35
	v_lshl_add_u64 v[32:33], v[48:49], 1, s[2:3]
	global_store_dwordx4 v[32:33], v[36:39], off
	v_lshlrev_b64 v[32:33], 10, v[144:145]
	v_or_b32_e32 v32, v32, v162
	s_and_b64 vcc, exec, s[0:1]
	v_lshl_add_u64 v[32:33], v[32:33], 0, s[22:23]
	s_cbranch_vccnz .LBB0_1062
	s_waitcnt vmcnt(15)
	v_pk_mov_b32 v[34:35], v[224:225], v[224:225] op_sel:[0,1] op_sel_hi:[0,1]
	v_pk_mov_b32 v[36:37], v[226:227], v[226:227] op_sel:[0,1] op_sel_hi:[0,1]
	v_lshlrev_b32_e32 v38, 16, v34
	v_and_b32_e32 v39, 0xffff0000, v34
	v_lshlrev_b32_e32 v34, 16, v35
	v_and_b32_e32 v35, 0xffff0000, v35
	v_lshlrev_b32_e32 v40, 16, v36
	v_and_b32_e32 v41, 0xffff0000, v36
	v_lshlrev_b32_e32 v36, 16, v37
	v_and_b32_e32 v37, 0xffff0000, v37
	v_pk_mul_f32 v[28:29], v[28:29], v[38:39]
	v_pk_mul_f32 v[30:31], v[30:31], v[34:35]
	v_pk_mul_f32 v[24:25], v[24:25], v[40:41]
	v_pk_mul_f32 v[26:27], v[26:27], v[36:37]
.LBB0_1062:
	v_cvt_pk_bf16_f32 v28, v28, v29
	v_cvt_pk_bf16_f32 v29, v30, v31
	v_cvt_pk_bf16_f32 v30, v24, v25
	v_cvt_pk_bf16_f32 v31, v26, v27
	v_lshl_add_u64 v[24:25], v[32:33], 1, s[2:3]
	s_and_b64 vcc, exec, s[0:1]
	v_or_b32_e32 v32, 0x80, v32
	global_store_dwordx4 v[24:25], v[28:31], off
	s_cbranch_vccnz .LBB0_1064
	s_waitcnt vmcnt(15)
	v_pk_mov_b32 v[24:25], v[228:229], v[228:229] op_sel:[0,1] op_sel_hi:[0,1]
	v_pk_mov_b32 v[26:27], v[230:231], v[230:231] op_sel:[0,1] op_sel_hi:[0,1]
	v_lshlrev_b32_e32 v28, 16, v24
	v_and_b32_e32 v29, 0xffff0000, v24
	v_lshlrev_b32_e32 v24, 16, v25
	v_and_b32_e32 v25, 0xffff0000, v25
	v_lshlrev_b32_e32 v30, 16, v26
	v_and_b32_e32 v31, 0xffff0000, v26
	v_lshlrev_b32_e32 v26, 16, v27
	v_and_b32_e32 v27, 0xffff0000, v27
	v_pk_mul_f32 v[20:21], v[20:21], v[28:29]
	v_pk_mul_f32 v[22:23], v[22:23], v[24:25]
	v_pk_mul_f32 v[16:17], v[16:17], v[30:31]
	v_pk_mul_f32 v[18:19], v[18:19], v[26:27]
.LBB0_1064:
	v_cvt_pk_bf16_f32 v20, v20, v21
	v_cvt_pk_bf16_f32 v21, v22, v23
	v_cvt_pk_bf16_f32 v22, v16, v17
	v_cvt_pk_bf16_f32 v23, v18, v19
	v_lshl_add_u64 v[16:17], v[32:33], 1, s[2:3]
	global_store_dwordx4 v[16:17], v[20:23], off
	v_lshlrev_b64 v[16:17], 10, v[144:145]
	v_or_b32_e32 v16, v16, v162
	s_and_b64 vcc, exec, s[0:1]
	v_lshl_add_u64 v[16:17], v[16:17], 0, s[24:25]
	s_cbranch_vccnz .LBB0_1066
	s_waitcnt vmcnt(15)
	v_pk_mov_b32 v[18:19], v[232:233], v[232:233] op_sel:[0,1] op_sel_hi:[0,1]
	v_pk_mov_b32 v[20:21], v[234:235], v[234:235] op_sel:[0,1] op_sel_hi:[0,1]
	v_lshlrev_b32_e32 v22, 16, v18
	v_and_b32_e32 v23, 0xffff0000, v18
	v_lshlrev_b32_e32 v18, 16, v19
	v_and_b32_e32 v19, 0xffff0000, v19
	v_lshlrev_b32_e32 v24, 16, v20
	v_and_b32_e32 v25, 0xffff0000, v20
	v_lshlrev_b32_e32 v20, 16, v21
	v_and_b32_e32 v21, 0xffff0000, v21
	v_pk_mul_f32 v[12:13], v[12:13], v[22:23]
	v_pk_mul_f32 v[14:15], v[14:15], v[18:19]
	v_pk_mul_f32 v[8:9], v[8:9], v[24:25]
	v_pk_mul_f32 v[10:11], v[10:11], v[20:21]
.LBB0_1066:
	v_cvt_pk_bf16_f32 v12, v12, v13
	v_cvt_pk_bf16_f32 v13, v14, v15
	v_cvt_pk_bf16_f32 v14, v8, v9
	v_cvt_pk_bf16_f32 v15, v10, v11
	v_lshl_add_u64 v[8:9], v[16:17], 1, s[2:3]
	s_cmp_gt_u32 s10, 3
	v_or_b32_e32 v16, 0x80, v16
	global_store_dwordx4 v[8:9], v[12:15], off
	s_cbranch_scc1 .LBB0_1068
	s_waitcnt vmcnt(15)
	v_pk_mov_b32 v[8:9], v[236:237], v[236:237] op_sel:[0,1] op_sel_hi:[0,1]
	v_pk_mov_b32 v[10:11], v[238:239], v[238:239] op_sel:[0,1] op_sel_hi:[0,1]
	v_lshlrev_b32_e32 v12, 16, v8
	v_and_b32_e32 v13, 0xffff0000, v8
	v_lshlrev_b32_e32 v8, 16, v9
	v_and_b32_e32 v9, 0xffff0000, v9
	v_lshlrev_b32_e32 v14, 16, v10
	v_and_b32_e32 v15, 0xffff0000, v10
	v_lshlrev_b32_e32 v10, 16, v11
	v_and_b32_e32 v11, 0xffff0000, v11
	v_pk_mul_f32 v[4:5], v[4:5], v[12:13]
	v_pk_mul_f32 v[6:7], v[6:7], v[8:9]
	v_pk_mul_f32 v[0:1], v[0:1], v[14:15]
	v_pk_mul_f32 v[2:3], v[2:3], v[10:11]
